# attention unit epilogue rewritten by hand: batched row-sum ds_swizzle reductions, LDS-transposed 16-byte O stores instead of 64 global_store_short per lane
# speedup vs baseline: 1.0045x; 1.0045x over previous
; #define SBAR() __builtin_amdgcn_sched_barrier(0)
; __device__ __forceinline__ void finishSM(f32x16& p0, f32x16& p1, float alpha, float& l_reg, bf16x8& pa0, bf16x8& pa1, bf16x8& pa2, bf16x8& pa3) {
; #pragma unroll
;   for (int r = 0; r < 16; ++r) p1[r] = __builtin_amdgcn_exp2f(p1[r]);
;   float ps = 0;
; #pragma unroll
;   for (int r = 0; r < 16; ++r) ps += p0[r];
; #pragma unroll
;   for (int r = 0; r < 16; ++r) ps += p1[r];
;   { auto rr = __builtin_amdgcn_permlane32_swap(__float_as_uint(ps), __float_as_uint(ps), false, false);
;     ps = __uint_as_float(rr[0]) + __uint_as_float(rr[1]); }
;   l_reg = l_reg * alpha + ps;
;     ...
;   PK4(p0, 0, pa0); PK4(p0, 8, pa1); PK4(p1, 0, pa2); PK4(p1, 8, pa3);
;     ...
; }
; template <int D0> __device__ __forceinline__ void pv_one(f32x16& od, int vb, bf16x8 pa0, bf16x8 pa1, bf16x8 pa2, bf16x8 pa3) {
;   const s16x4 l0 = tr_read<v_rd_off(D0, 0, 0)>(vb), h0 = tr_read<v_rd_off(D0, 0, 1)>(vb), l1 = tr_read<v_rd_off(D0, 1, 0)>(vb), h1 = tr_read<v_rd_off(D0, 1, 1)>(vb);
;   const s16x4 l2 = tr_read<v_rd_off(D0, 2, 0)>(vb), h2 = tr_read<v_rd_off(D0, 2, 1)>(vb), l3 = tr_read<v_rd_off(D0, 3, 0)>(vb), h3 = tr_read<v_rd_off(D0, 3, 1)>(vb);
;   asm volatile("s_waitcnt lgkmcnt(0)" ::: "memory"); SBAR();
;     ...
;   od = __builtin_amdgcn_mfma_f32_32x32x16_bf16(pa0, PK(l0, h0), od, 0, 0, 0);
;   od = __builtin_amdgcn_mfma_f32_32x32x16_bf16(pa1, PK(l1, h1), od, 0, 0, 0);
;   od = __builtin_amdgcn_mfma_f32_32x32x16_bf16(pa2, PK(l2, h2), od, 0, 0, 0);
;   od = __builtin_amdgcn_mfma_f32_32x32x16_bf16(pa3, PK(l3, h3), od, 0, 0, 0);
;     ...
; }
; __device__ __forceinline__ void pv_d0(f32x16* o, int vb, bf16x8 pa0, bf16x8 pa1, bf16x8 pa2, bf16x8 pa3) {
;   pv_one<0>(o[0], vb, pa0, pa1, pa2, pa3); pv_one<1>(o[1], vb, pa0, pa1, pa2, pa3); pv_one<2>(o[2], vb, pa0, pa1, pa2, pa3); pv_one<3>(o[3], vb, pa0, pa1, pa2, pa3);
; }
.LBB0_1166:
	v_cndmask_b32_e64 v97, v97, v223, s[4:5]
	v_mul_f32_e32 v97, 0xbdd53b94, v97
	v_fmamk_f32 v80, v80, 0x3dd53b94, v97
	v_fmamk_f32 v81, v81, 0x3dd53b94, v97
	v_fmamk_f32 v98, v82, 0x3dd53b94, v97
	v_exp_f32_e32 v82, v80
	v_fmamk_f32 v99, v84, 0x3dd53b94, v97
	v_exp_f32_e32 v84, v81
	v_fmamk_f32 v83, v83, 0x3dd53b94, v97
	v_exp_f32_e32 v80, v98
	v_fmamk_f32 v64, v64, 0x3dd53b94, v97
	v_exp_f32_e32 v83, v83
	v_fmamk_f32 v100, v85, 0x3dd53b94, v97
	v_fmamk_f32 v111, v94, 0x3dd53b94, v97
	v_fmamk_f32 v94, v75, 0x3dd53b94, v97
	v_exp_f32_e32 v75, v99
	v_exp_f32_e32 v98, v64
	v_add_f32_e32 v64, 0, v82
	v_fmamk_f32 v101, v86, 0x3dd53b94, v97
	v_exp_f32_e32 v81, v100
	v_add_f32_e32 v64, v84, v64
	v_fmamk_f32 v102, v87, 0x3dd53b94, v97
	v_fmamk_f32 v110, v93, 0x3dd53b94, v97
	v_fmamk_f32 v93, v74, 0x3dd53b94, v97
	v_exp_f32_e32 v74, v101
	v_add_f32_e32 v64, v80, v64
	v_fmamk_f32 v103, v88, 0x3dd53b94, v97
	v_fmamk_f32 v112, v95, 0x3dd53b94, v97
	v_fmamk_f32 v95, v76, 0x3dd53b94, v97
	v_exp_f32_e32 v76, v102
	v_add_f32_e32 v64, v83, v64
	v_fmamk_f32 v104, v89, 0x3dd53b94, v97
	v_fmamk_f32 v105, v90, 0x3dd53b94, v97
	v_fmamk_f32 v90, v71, 0x3dd53b94, v97
	v_exp_f32_e32 v71, v103
	v_add_f32_e32 v64, v75, v64
	v_fmamk_f32 v107, v92, 0x3dd53b94, v97
	v_fmamk_f32 v92, v73, 0x3dd53b94, v97
	v_exp_f32_e32 v73, v104
	v_add_f32_e32 v64, v81, v64
	v_fmamk_f32 v106, v91, 0x3dd53b94, v97
	v_fmamk_f32 v88, v69, 0x3dd53b94, v97
	v_exp_f32_e32 v69, v105
	v_add_f32_e32 v64, v74, v64
	v_fmamk_f32 v91, v72, 0x3dd53b94, v97
	v_exp_f32_e32 v72, v106
	v_add_f32_e32 v64, v76, v64
	v_fmamk_f32 v86, v67, 0x3dd53b94, v97
	v_exp_f32_e32 v67, v107
	v_add_f32_e32 v64, v71, v64
	v_fmamk_f32 v89, v70, 0x3dd53b94, v97
	v_exp_f32_e32 v70, v110
	v_add_f32_e32 v64, v73, v64
	v_fmamk_f32 v85, v66, 0x3dd53b94, v97
	v_exp_f32_e32 v66, v111
	v_add_f32_e32 v64, v69, v64
	v_fmamk_f32 v87, v68, 0x3dd53b94, v97
	v_exp_f32_e32 v68, v112
	v_add_f32_e32 v64, v72, v64
	v_fmamk_f32 v65, v65, 0x3dd53b94, v97
	v_add_f32_e32 v64, v67, v64
	v_exp_f32_e32 v99, v65
	v_add_f32_e32 v64, v70, v64
	v_exp_f32_e32 v85, v85
	v_add_f32_e32 v64, v66, v64
	v_exp_f32_e32 v86, v86
	v_add_f32_e32 v64, v68, v64
	v_exp_f32_e32 v87, v87
	v_add_f32_e32 v64, v98, v64
	v_exp_f32_e32 v88, v88
	v_add_f32_e32 v64, v99, v64
	v_exp_f32_e32 v89, v89
	v_add_f32_e32 v64, v85, v64
	v_exp_f32_e32 v90, v90
	v_add_f32_e32 v64, v86, v64
	v_exp_f32_e32 v91, v91
	v_add_f32_e32 v64, v87, v64
	v_exp_f32_e32 v92, v92
	v_add_f32_e32 v64, v88, v64
	v_exp_f32_e32 v93, v93
	v_add_f32_e32 v64, v89, v64
	v_exp_f32_e32 v94, v94
	v_add_f32_e32 v64, v90, v64
	v_fmamk_f32 v77, v77, 0x3dd53b94, v97
	v_exp_f32_e32 v95, v95
	v_add_f32_e32 v64, v91, v64
	v_fmamk_f32 v78, v78, 0x3dd53b94, v97
	v_exp_f32_e32 v100, v77
	v_add_f32_e32 v64, v92, v64
	v_fmac_f32_e32 v97, 0x3dd53b94, v79
	v_exp_f32_e32 v101, v78
	v_add_f32_e32 v64, v93, v64
	v_exp_f32_e32 v97, v97
	v_add_f32_e32 v64, v94, v64
	v_add_f32_e32 v64, v95, v64
	v_add_f32_e32 v64, v100, v64
	v_add_f32_e32 v64, v101, v64
	v_add_f32_e32 v64, v97, v64
	v_mov_b32_e32 v65, v64
	s_nop 1
	v_permlane32_swap_b32_e32 v64, v65
	v_cvt_pk_bf16_f32 v78, v82, v84
	v_cvt_pk_bf16_f32 v79, v80, v83
	v_cvt_pk_bf16_f32 v80, v75, v81
	v_cvt_pk_bf16_f32 v81, v74, v76
	v_cvt_pk_bf16_f32 v74, v71, v73
	v_cvt_pk_bf16_f32 v75, v69, v72
	v_cvt_pk_bf16_f32 v76, v67, v70
	v_cvt_pk_bf16_f32 v77, v66, v68
	v_cvt_pk_bf16_f32 v66, v98, v99
	v_cvt_pk_bf16_f32 v67, v85, v86
	v_cvt_pk_bf16_f32 v68, v87, v88
	v_cvt_pk_bf16_f32 v69, v89, v90
	v_cvt_pk_bf16_f32 v70, v91, v92
	v_cvt_pk_bf16_f32 v71, v93, v94
	v_cvt_pk_bf16_f32 v72, v95, v100
	v_cvt_pk_bf16_f32 v73, v101, v97
	s_nop 0
	v_permlane32_swap_b32_e32 v78, v80
	v_permlane32_swap_b32_e32 v79, v81
	v_permlane32_swap_b32_e32 v74, v76
	v_permlane32_swap_b32_e32 v75, v77
	v_permlane32_swap_b32_e32 v66, v68
	v_permlane32_swap_b32_e32 v67, v69
	v_permlane32_swap_b32_e32 v70, v72
	v_permlane32_swap_b32_e32 v71, v73
	ds_read_b64_tr_b16 v[82:83], v196 offset:0
	ds_read_b64_tr_b16 v[84:85], v196 offset:0x800
	ds_read_b64_tr_b16 v[86:87], v196 offset:0x1000
	ds_read_b64_tr_b16 v[88:89], v196 offset:0x1800
	ds_read_b64_tr_b16 v[90:91], v196 offset:0x2000
	ds_read_b64_tr_b16 v[92:93], v196 offset:0x2800
	ds_read_b64_tr_b16 v[98:99], v196 offset:0x3000
	ds_read_b64_tr_b16 v[100:101], v196 offset:0x3800
	s_waitcnt lgkmcnt(0)
	s_nop 0
	v_mfma_f32_32x32x16_bf16 v[0:15], v[78:81], v[82:85], v[0:15]
	ds_read_b64_tr_b16 v[82:83], v196 offset:0x200
	ds_read_b64_tr_b16 v[84:85], v196 offset:0xa00
	v_mfma_f32_32x32x16_bf16 v[0:15], v[74:77], v[86:89], v[0:15]
	ds_read_b64_tr_b16 v[86:87], v196 offset:0x1200
	ds_read_b64_tr_b16 v[88:89], v196 offset:0x1a00
	v_mfma_f32_32x32x16_bf16 v[0:15], v[66:69], v[90:93], v[0:15]
	ds_read_b64_tr_b16 v[90:91], v196 offset:0x2200
	ds_read_b64_tr_b16 v[92:93], v196 offset:0x2a00
	ds_read_b64_tr_b16 v[102:103], v196 offset:0x3200
	ds_read_b64_tr_b16 v[104:105], v196 offset:0x3a00
	s_waitcnt lgkmcnt(0)
	v_mfma_f32_32x32x16_bf16 v[0:15], v[70:73], v[98:101], v[0:15]
	v_mfma_f32_32x32x16_bf16 v[48:63], v[78:81], v[82:85], v[48:63]
	ds_read_b64_tr_b16 v[82:83], v196 offset:0x400
	ds_read_b64_tr_b16 v[84:85], v196 offset:0xc00
	v_mfma_f32_32x32x16_bf16 v[48:63], v[74:77], v[86:89], v[48:63]
	ds_read_b64_tr_b16 v[86:87], v196 offset:0x1400
	ds_read_b64_tr_b16 v[88:89], v196 offset:0x1c00
	v_mfma_f32_32x32x16_bf16 v[48:63], v[66:69], v[90:93], v[48:63]
	ds_read_b64_tr_b16 v[90:91], v196 offset:0x2400
	ds_read_b64_tr_b16 v[92:93], v196 offset:0x2c00
	ds_read_b64_tr_b16 v[98:99], v196 offset:0x3400
	ds_read_b64_tr_b16 v[100:101], v196 offset:0x3c00
	s_waitcnt lgkmcnt(0)
; __device__ __forceinline__ int crow(int r, int hi) { return (r & 3) + 8 * (r >> 2) + 4 * hi; }
; __device__ __forceinline__ unsigned cvtpk(float lo, float hi) { unsigned r; asm volatile("v_cvt_pk_bf16_f32 %0, %1, %2" : "=v"(r) : "v"(lo), "v"(hi)); return r; }
; __device__ __forceinline__ void attn_dense_body(const bf16* __restrict__ Qb, const bf16* __restrict__ Kn, const bf16* __restrict__ Kr, const bf16* __restrict__ Vh,
;                                                 bf16* __restrict__ Ob, pg8::u64* ssa, int seq, char* lds, const int wv) {
;     ...
;   if (hi == 0) li_l[r32] = l_reg; asm volatile("s_waitcnt lgkmcnt(0)" ::: "memory");
;   float rli[16];
; #pragma unroll
;   for (int r = 0; r < 16; ++r) rli[r] = __builtin_amdgcn_rcpf(li_l[crow(r, hi)]);
;   bf16* Ow = Ob + (long)(wid * QBLK) * LDO;
; #pragma unroll
;   for (int r = 0; r < 16; ++r) { int orow = crow(r, hi);
;     float sq = 0.f;
; #pragma unroll
;     for (int d0 = 0; d0 < 4; ++d0) { const float v = o[d0][r] * rli[r]; sq += v * v; Ow[(long)orow * LDO + d0 * 32 + r32] = (bf16)(cvtpk(v, 0.f) & 0xffffu); }
	v_mfma_f32_32x32x16_bf16 v[48:63], v[70:73], v[102:105], v[48:63]
	v_mfma_f32_32x32x16_bf16 v[32:47], v[78:81], v[82:85], v[32:47]
	ds_read_b64_tr_b16 v[82:83], v196 offset:0x600
	ds_read_b64_tr_b16 v[84:85], v196 offset:0xe00
	v_mfma_f32_32x32x16_bf16 v[32:47], v[74:77], v[86:89], v[32:47]
	ds_read_b64_tr_b16 v[86:87], v196 offset:0x1600
	ds_read_b64_tr_b16 v[88:89], v196 offset:0x1e00
	v_mfma_f32_32x32x16_bf16 v[32:47], v[66:69], v[90:93], v[32:47]
	ds_read_b64_tr_b16 v[90:91], v196 offset:0x2600
	ds_read_b64_tr_b16 v[92:93], v196 offset:0x2e00
	ds_read_b64_tr_b16 v[102:103], v196 offset:0x3600
	ds_read_b64_tr_b16 v[104:105], v196 offset:0x3e00
	s_waitcnt lgkmcnt(0)
	v_mfma_f32_32x32x16_bf16 v[32:47], v[70:73], v[98:101], v[32:47]
	v_mfma_f32_32x32x16_bf16 v[16:31], v[78:81], v[82:85], v[16:31]
	v_mfma_f32_32x32x16_bf16 v[16:31], v[74:77], v[86:89], v[16:31]
	v_mfma_f32_32x32x16_bf16 v[16:31], v[66:69], v[90:93], v[16:31]
	v_mfma_f32_32x32x16_bf16 v[16:31], v[70:73], v[102:105], v[16:31]
	s_and_saveexec_b64 s[4:5], s[2:3]
	v_add_f32_e32 v66, v108, v109
	v_fmac_f32_e32 v66, v195, v164
	v_add_f32_e32 v64, v64, v65
	v_fmac_f32_e32 v64, v66, v96
	ds_write_b32 v194, v64
	s_or_b64 exec, exec, s[4:5]
	s_waitcnt lgkmcnt(0)
	v_add_u32_e32 v64, v171, v168
	ds_read_b128 v[76:79], v64
	ds_read_b128 v[72:75], v64 offset:32
	ds_read_b128 v[68:71], v64 offset:64
	ds_read_b128 v[64:67], v64 offset:96
	s_lshl_b64 s[2:3], s[58:59], 3
	s_add_u32 s2, s29, s2
	s_addc_u32 s3, s31, s3
	s_lshl_b64 s[4:5], s[58:59], 12
	s_add_u32 s4, s16, s4
	s_addc_u32 s5, s17, s5
	s_lshl_b32 s20, s80, 8
	s_add_u32 s4, s4, s20
	s_addc_u32 s5, s5, 0
	v_ashrrev_i32_e32 v171, 31, v170
	v_lshl_add_u64 v[80:81], v[170:171], 3, s[2:3]
	v_lshlrev_b32_e32 v82, 5, v192
	v_mov_b32_e32 v83, 0
	v_lshl_add_u64 v[80:81], v[80:81], 0, v[82:83]
	v_lshlrev_b32_e32 v84, 12, v170
	v_lshl_add_u32 v84, v193, 1, v84
	v_lshl_add_u32 v84, v192, 14, v84
	v_cmp_eq_u32_e32 vcc, 0, v193
	s_waitcnt lgkmcnt(0)
	v_rcp_f32_e32 v76, v76
	v_rcp_f32_e32 v77, v77
	v_rcp_f32_e32 v78, v78
	v_rcp_f32_e32 v79, v79
	v_rcp_f32_e32 v72, v72
	v_rcp_f32_e32 v73, v73
	v_rcp_f32_e32 v74, v74
	v_rcp_f32_e32 v75, v75
	v_rcp_f32_e32 v68, v68
	v_rcp_f32_e32 v69, v69
	v_rcp_f32_e32 v70, v70
	v_rcp_f32_e32 v71, v71
	v_rcp_f32_e32 v64, v64
	v_rcp_f32_e32 v65, v65
	v_rcp_f32_e32 v66, v66
	v_rcp_f32_e32 v67, v67
	s_nop 0
	v_mul_f32_e32 v0, v0, v76
	v_mul_f32_e32 v48, v48, v76
	v_mul_f32_e32 v32, v32, v76
	v_mul_f32_e32 v16, v16, v76
	v_mul_f32_e32 v1, v1, v77
	v_mul_f32_e32 v49, v49, v77
	v_mul_f32_e32 v33, v33, v77
	v_mul_f32_e32 v17, v17, v77
	v_mul_f32_e32 v2, v2, v78
	v_mul_f32_e32 v50, v50, v78
	v_mul_f32_e32 v34, v34, v78
	v_mul_f32_e32 v18, v18, v78
	v_mul_f32_e32 v3, v3, v79
	v_mul_f32_e32 v51, v51, v79
	v_mul_f32_e32 v35, v35, v79
	v_mul_f32_e32 v19, v19, v79
	v_mul_f32_e32 v4, v4, v72
	v_mul_f32_e32 v52, v52, v72
	v_mul_f32_e32 v36, v36, v72
	v_mul_f32_e32 v20, v20, v72
	v_mul_f32_e32 v5, v5, v73
	v_mul_f32_e32 v53, v53, v73
	v_mul_f32_e32 v37, v37, v73
	v_mul_f32_e32 v21, v21, v73
	v_mul_f32_e32 v6, v6, v74
	v_mul_f32_e32 v54, v54, v74
	v_mul_f32_e32 v38, v38, v74
	v_mul_f32_e32 v22, v22, v74
	v_mul_f32_e32 v7, v7, v75
	v_mul_f32_e32 v55, v55, v75
	v_mul_f32_e32 v39, v39, v75
	v_mul_f32_e32 v23, v23, v75
	v_mul_f32_e32 v8, v8, v68
	v_mul_f32_e32 v56, v56, v68
	v_mul_f32_e32 v40, v40, v68
	v_mul_f32_e32 v24, v24, v68
	v_mul_f32_e32 v9, v9, v69
	v_mul_f32_e32 v57, v57, v69
	v_mul_f32_e32 v41, v41, v69
	v_mul_f32_e32 v25, v25, v69
	v_mul_f32_e32 v10, v10, v70
	v_mul_f32_e32 v58, v58, v70
	v_mul_f32_e32 v42, v42, v70
	v_mul_f32_e32 v26, v26, v70
	v_mul_f32_e32 v11, v11, v71
	v_mul_f32_e32 v59, v59, v71
	v_mul_f32_e32 v43, v43, v71
	v_mul_f32_e32 v27, v27, v71
	v_mul_f32_e32 v12, v12, v64
	v_mul_f32_e32 v60, v60, v64
	v_mul_f32_e32 v44, v44, v64
	v_mul_f32_e32 v28, v28, v64
	v_mul_f32_e32 v13, v13, v65
	v_mul_f32_e32 v61, v61, v65
	v_mul_f32_e32 v45, v45, v65
	v_mul_f32_e32 v29, v29, v65
	v_mul_f32_e32 v14, v14, v66
	v_mul_f32_e32 v62, v62, v66
	v_mul_f32_e32 v46, v46, v66
	v_mul_f32_e32 v30, v30, v66
	v_mul_f32_e32 v15, v15, v67
	v_mul_f32_e32 v63, v63, v67
	v_mul_f32_e32 v47, v47, v67
	v_mul_f32_e32 v31, v31, v67
	v_mul_f32_e32 v96, v0, v0
	v_fmac_f32_e32 v96, v48, v48
	v_fmac_f32_e32 v96, v32, v32
	v_fmac_f32_e32 v96, v16, v16
	v_mul_f32_e32 v97, v1, v1
	v_fmac_f32_e32 v97, v49, v49
	v_fmac_f32_e32 v97, v33, v33
	v_fmac_f32_e32 v97, v17, v17
	v_mul_f32_e32 v98, v2, v2
	v_fmac_f32_e32 v98, v50, v50
	v_fmac_f32_e32 v98, v34, v34
	v_fmac_f32_e32 v98, v18, v18
	v_mul_f32_e32 v99, v3, v3
	v_fmac_f32_e32 v99, v51, v51
	v_fmac_f32_e32 v99, v35, v35
	v_fmac_f32_e32 v99, v19, v19
	v_mul_f32_e32 v100, v4, v4
	v_fmac_f32_e32 v100, v52, v52
	v_fmac_f32_e32 v100, v36, v36
	v_fmac_f32_e32 v100, v20, v20
	v_mul_f32_e32 v101, v5, v5
	v_fmac_f32_e32 v101, v53, v53
	v_fmac_f32_e32 v101, v37, v37
	v_fmac_f32_e32 v101, v21, v21
	v_mul_f32_e32 v102, v6, v6
	v_fmac_f32_e32 v102, v54, v54
	v_fmac_f32_e32 v102, v38, v38
	v_fmac_f32_e32 v102, v22, v22
	v_mul_f32_e32 v103, v7, v7
	v_fmac_f32_e32 v103, v55, v55
	v_fmac_f32_e32 v103, v39, v39
	v_fmac_f32_e32 v103, v23, v23
	v_mul_f32_e32 v104, v8, v8
	v_fmac_f32_e32 v104, v56, v56
	v_fmac_f32_e32 v104, v40, v40
	v_fmac_f32_e32 v104, v24, v24
	v_mul_f32_e32 v105, v9, v9
	v_fmac_f32_e32 v105, v57, v57
	v_fmac_f32_e32 v105, v41, v41
	v_fmac_f32_e32 v105, v25, v25
	v_mul_f32_e32 v106, v10, v10
	v_fmac_f32_e32 v106, v58, v58
	v_fmac_f32_e32 v106, v42, v42
	v_fmac_f32_e32 v106, v26, v26
	v_mul_f32_e32 v107, v11, v11
	v_fmac_f32_e32 v107, v59, v59
	v_fmac_f32_e32 v107, v43, v43
	v_fmac_f32_e32 v107, v27, v27
	v_mul_f32_e32 v108, v12, v12
	v_fmac_f32_e32 v108, v60, v60
	v_fmac_f32_e32 v108, v44, v44
	v_fmac_f32_e32 v108, v28, v28
	v_mul_f32_e32 v109, v13, v13
	v_fmac_f32_e32 v109, v61, v61
	v_fmac_f32_e32 v109, v45, v45
	v_fmac_f32_e32 v109, v29, v29
	v_mul_f32_e32 v110, v14, v14
	v_fmac_f32_e32 v110, v62, v62
	v_fmac_f32_e32 v110, v46, v46
	v_fmac_f32_e32 v110, v30, v30
	v_mul_f32_e32 v111, v15, v15
	v_fmac_f32_e32 v111, v63, v63
	v_fmac_f32_e32 v111, v47, v47
	v_fmac_f32_e32 v111, v31, v31
	ds_swizzle_b32 v112, v96 offset:swizzle(SWAP,1)
	ds_swizzle_b32 v113, v97 offset:swizzle(SWAP,1)
	ds_swizzle_b32 v114, v98 offset:swizzle(SWAP,1)
	ds_swizzle_b32 v115, v99 offset:swizzle(SWAP,1)
	ds_swizzle_b32 v116, v100 offset:swizzle(SWAP,1)
	ds_swizzle_b32 v117, v101 offset:swizzle(SWAP,1)
	ds_swizzle_b32 v118, v102 offset:swizzle(SWAP,1)
	ds_swizzle_b32 v119, v103 offset:swizzle(SWAP,1)
	s_waitcnt lgkmcnt(0)
; template <int MASK> __device__ __forceinline__ float xor_get(float v) { return __int_as_float(__builtin_amdgcn_ds_swizzle(__float_as_int(v), 0x1F | (MASK << 10))); }
; __device__ __forceinline__ void ss_add(u64* p, float v) { atomicAdd(p, (u64)(v * SSFIX)); }
; __device__ __forceinline__ int crow(int r, int hi) { return (r & 3) + 8 * (r >> 2) + 4 * hi; }
; __device__ __forceinline__ unsigned cvtpk(float lo, float hi) { unsigned r; asm volatile("v_cvt_pk_bf16_f32 %0, %1, %2" : "=v"(r) : "v"(lo), "v"(hi)); return r; }
; __device__ __forceinline__ void attn_dense_body(const bf16* __restrict__ Qb, const bf16* __restrict__ Kn, const bf16* __restrict__ Kr, const bf16* __restrict__ Vh,
;                                                 bf16* __restrict__ Ob, pg8::u64* ssa, int seq, char* lds, const int wv) {
;     ...
;   for (int r = 0; r < 16; ++r) { int orow = crow(r, hi);
;     float sq = 0.f;
; #pragma unroll
;     for (int d0 = 0; d0 < 4; ++d0) { const float v = o[d0][r] * rli[r]; sq += v * v; Ow[(long)orow * LDO + d0 * 32 + r32] = (bf16)(cvtpk(v, 0.f) & 0xffffu); }
;     sq += xor_get<1>(sq); sq += xor_get<2>(sq); sq += xor_get<4>(sq); sq += xor_get<8>(sq); sq += xor_get<16>(sq);
;     if (r32 == 0) pg8::ss_add(ssa + wid * QBLK + orow, sq); }
	v_add_f32_e32 v96, v96, v112
	v_add_f32_e32 v97, v97, v113
	v_add_f32_e32 v98, v98, v114
	v_add_f32_e32 v99, v99, v115
	v_add_f32_e32 v100, v100, v116
	v_add_f32_e32 v101, v101, v117
	v_add_f32_e32 v102, v102, v118
	v_add_f32_e32 v103, v103, v119
	ds_swizzle_b32 v112, v104 offset:swizzle(SWAP,1)
	ds_swizzle_b32 v113, v105 offset:swizzle(SWAP,1)
	ds_swizzle_b32 v114, v106 offset:swizzle(SWAP,1)
	ds_swizzle_b32 v115, v107 offset:swizzle(SWAP,1)
	ds_swizzle_b32 v116, v108 offset:swizzle(SWAP,1)
	ds_swizzle_b32 v117, v109 offset:swizzle(SWAP,1)
	ds_swizzle_b32 v118, v110 offset:swizzle(SWAP,1)
	ds_swizzle_b32 v119, v111 offset:swizzle(SWAP,1)
	s_waitcnt lgkmcnt(0)
	v_add_f32_e32 v104, v104, v112
	v_add_f32_e32 v105, v105, v113
	v_add_f32_e32 v106, v106, v114
	v_add_f32_e32 v107, v107, v115
	v_add_f32_e32 v108, v108, v116
	v_add_f32_e32 v109, v109, v117
	v_add_f32_e32 v110, v110, v118
	v_add_f32_e32 v111, v111, v119
	ds_swizzle_b32 v112, v96 offset:swizzle(SWAP,2)
	ds_swizzle_b32 v113, v97 offset:swizzle(SWAP,2)
	ds_swizzle_b32 v114, v98 offset:swizzle(SWAP,2)
	ds_swizzle_b32 v115, v99 offset:swizzle(SWAP,2)
	ds_swizzle_b32 v116, v100 offset:swizzle(SWAP,2)
	ds_swizzle_b32 v117, v101 offset:swizzle(SWAP,2)
	ds_swizzle_b32 v118, v102 offset:swizzle(SWAP,2)
	ds_swizzle_b32 v119, v103 offset:swizzle(SWAP,2)
	s_waitcnt lgkmcnt(0)
	v_add_f32_e32 v96, v96, v112
	v_add_f32_e32 v97, v97, v113
	v_add_f32_e32 v98, v98, v114
	v_add_f32_e32 v99, v99, v115
	v_add_f32_e32 v100, v100, v116
	v_add_f32_e32 v101, v101, v117
	v_add_f32_e32 v102, v102, v118
	v_add_f32_e32 v103, v103, v119
	ds_swizzle_b32 v112, v104 offset:swizzle(SWAP,2)
	ds_swizzle_b32 v113, v105 offset:swizzle(SWAP,2)
	ds_swizzle_b32 v114, v106 offset:swizzle(SWAP,2)
	ds_swizzle_b32 v115, v107 offset:swizzle(SWAP,2)
	ds_swizzle_b32 v116, v108 offset:swizzle(SWAP,2)
	ds_swizzle_b32 v117, v109 offset:swizzle(SWAP,2)
	ds_swizzle_b32 v118, v110 offset:swizzle(SWAP,2)
	ds_swizzle_b32 v119, v111 offset:swizzle(SWAP,2)
	s_waitcnt lgkmcnt(0)
	v_add_f32_e32 v104, v104, v112
	v_add_f32_e32 v105, v105, v113
	v_add_f32_e32 v106, v106, v114
	v_add_f32_e32 v107, v107, v115
	v_add_f32_e32 v108, v108, v116
	v_add_f32_e32 v109, v109, v117
	v_add_f32_e32 v110, v110, v118
	v_add_f32_e32 v111, v111, v119
	ds_swizzle_b32 v112, v96 offset:swizzle(SWAP,4)
	ds_swizzle_b32 v113, v97 offset:swizzle(SWAP,4)
	ds_swizzle_b32 v114, v98 offset:swizzle(SWAP,4)
	ds_swizzle_b32 v115, v99 offset:swizzle(SWAP,4)
	ds_swizzle_b32 v116, v100 offset:swizzle(SWAP,4)
	ds_swizzle_b32 v117, v101 offset:swizzle(SWAP,4)
	ds_swizzle_b32 v118, v102 offset:swizzle(SWAP,4)
	ds_swizzle_b32 v119, v103 offset:swizzle(SWAP,4)
	s_waitcnt lgkmcnt(0)
	v_add_f32_e32 v96, v96, v112
	v_add_f32_e32 v97, v97, v113
	v_add_f32_e32 v98, v98, v114
	v_add_f32_e32 v99, v99, v115
	v_add_f32_e32 v100, v100, v116
	v_add_f32_e32 v101, v101, v117
	v_add_f32_e32 v102, v102, v118
	v_add_f32_e32 v103, v103, v119
	ds_swizzle_b32 v112, v104 offset:swizzle(SWAP,4)
	ds_swizzle_b32 v113, v105 offset:swizzle(SWAP,4)
	ds_swizzle_b32 v114, v106 offset:swizzle(SWAP,4)
	ds_swizzle_b32 v115, v107 offset:swizzle(SWAP,4)
	ds_swizzle_b32 v116, v108 offset:swizzle(SWAP,4)
	ds_swizzle_b32 v117, v109 offset:swizzle(SWAP,4)
	ds_swizzle_b32 v118, v110 offset:swizzle(SWAP,4)
	ds_swizzle_b32 v119, v111 offset:swizzle(SWAP,4)
	s_waitcnt lgkmcnt(0)
	v_add_f32_e32 v104, v104, v112
	v_add_f32_e32 v105, v105, v113
	v_add_f32_e32 v106, v106, v114
	v_add_f32_e32 v107, v107, v115
	v_add_f32_e32 v108, v108, v116
	v_add_f32_e32 v109, v109, v117
	v_add_f32_e32 v110, v110, v118
	v_add_f32_e32 v111, v111, v119
	ds_swizzle_b32 v112, v96 offset:swizzle(SWAP,8)
	ds_swizzle_b32 v113, v97 offset:swizzle(SWAP,8)
	ds_swizzle_b32 v114, v98 offset:swizzle(SWAP,8)
	ds_swizzle_b32 v115, v99 offset:swizzle(SWAP,8)
	ds_swizzle_b32 v116, v100 offset:swizzle(SWAP,8)
	ds_swizzle_b32 v117, v101 offset:swizzle(SWAP,8)
	ds_swizzle_b32 v118, v102 offset:swizzle(SWAP,8)
	ds_swizzle_b32 v119, v103 offset:swizzle(SWAP,8)
	s_waitcnt lgkmcnt(0)
	v_add_f32_e32 v96, v96, v112
	v_add_f32_e32 v97, v97, v113
	v_add_f32_e32 v98, v98, v114
	v_add_f32_e32 v99, v99, v115
	v_add_f32_e32 v100, v100, v116
	v_add_f32_e32 v101, v101, v117
	v_add_f32_e32 v102, v102, v118
	v_add_f32_e32 v103, v103, v119
	ds_swizzle_b32 v112, v104 offset:swizzle(SWAP,8)
	ds_swizzle_b32 v113, v105 offset:swizzle(SWAP,8)
	ds_swizzle_b32 v114, v106 offset:swizzle(SWAP,8)
	ds_swizzle_b32 v115, v107 offset:swizzle(SWAP,8)
	ds_swizzle_b32 v116, v108 offset:swizzle(SWAP,8)
	ds_swizzle_b32 v117, v109 offset:swizzle(SWAP,8)
	ds_swizzle_b32 v118, v110 offset:swizzle(SWAP,8)
	ds_swizzle_b32 v119, v111 offset:swizzle(SWAP,8)
	s_waitcnt lgkmcnt(0)
	v_add_f32_e32 v104, v104, v112
	v_add_f32_e32 v105, v105, v113
	v_add_f32_e32 v106, v106, v114
	v_add_f32_e32 v107, v107, v115
	v_add_f32_e32 v108, v108, v116
	v_add_f32_e32 v109, v109, v117
	v_add_f32_e32 v110, v110, v118
	v_add_f32_e32 v111, v111, v119
	ds_swizzle_b32 v112, v96 offset:swizzle(SWAP,16)
	ds_swizzle_b32 v113, v97 offset:swizzle(SWAP,16)
	ds_swizzle_b32 v114, v98 offset:swizzle(SWAP,16)
	ds_swizzle_b32 v115, v99 offset:swizzle(SWAP,16)
	ds_swizzle_b32 v116, v100 offset:swizzle(SWAP,16)
	ds_swizzle_b32 v117, v101 offset:swizzle(SWAP,16)
	ds_swizzle_b32 v118, v102 offset:swizzle(SWAP,16)
	ds_swizzle_b32 v119, v103 offset:swizzle(SWAP,16)
	s_waitcnt lgkmcnt(0)
; __device__ __forceinline__ int crow(int r, int hi) { return (r & 3) + 8 * (r >> 2) + 4 * hi; }
; __device__ __forceinline__ unsigned cvtpk(float lo, float hi) { unsigned r; asm volatile("v_cvt_pk_bf16_f32 %0, %1, %2" : "=v"(r) : "v"(lo), "v"(hi)); return r; }
; __device__ __forceinline__ void attn_dense_body(const bf16* __restrict__ Qb, const bf16* __restrict__ Kn, const bf16* __restrict__ Kr, const bf16* __restrict__ Vh,
;                                                 bf16* __restrict__ Ob, pg8::u64* ssa, int seq, char* lds, const int wv) {
;     ...
;   for (int r = 0; r < 16; ++r) { int orow = crow(r, hi);
;     float sq = 0.f;
; #pragma unroll
;     for (int d0 = 0; d0 < 4; ++d0) { const float v = o[d0][r] * rli[r]; sq += v * v; Ow[(long)orow * LDO + d0 * 32 + r32] = (bf16)(cvtpk(v, 0.f) & 0xffffu); }
	v_add_f32_e32 v96, v96, v112
	v_add_f32_e32 v97, v97, v113
	v_add_f32_e32 v98, v98, v114
	v_add_f32_e32 v99, v99, v115
	v_add_f32_e32 v100, v100, v116
	v_add_f32_e32 v101, v101, v117
	v_add_f32_e32 v102, v102, v118
	v_add_f32_e32 v103, v103, v119
	ds_swizzle_b32 v112, v104 offset:swizzle(SWAP,16)
	ds_swizzle_b32 v113, v105 offset:swizzle(SWAP,16)
	ds_swizzle_b32 v114, v106 offset:swizzle(SWAP,16)
	ds_swizzle_b32 v115, v107 offset:swizzle(SWAP,16)
	ds_swizzle_b32 v116, v108 offset:swizzle(SWAP,16)
	ds_swizzle_b32 v117, v109 offset:swizzle(SWAP,16)
	ds_swizzle_b32 v118, v110 offset:swizzle(SWAP,16)
	ds_swizzle_b32 v119, v111 offset:swizzle(SWAP,16)
	s_waitcnt lgkmcnt(0)
	v_add_f32_e32 v104, v104, v112
	v_add_f32_e32 v105, v105, v113
	v_add_f32_e32 v106, v106, v114
	v_add_f32_e32 v107, v107, v115
	v_add_f32_e32 v108, v108, v116
	v_add_f32_e32 v109, v109, v117
	v_add_f32_e32 v110, v110, v118
	v_add_f32_e32 v111, v111, v119
	s_lshl_b32 s98, s33, 7
	s_mov_b32 s99, 0xd000
	s_cmp_lt_u32 s33, 0x100
	s_cselect_b32 s99, 0x8000, s99
	s_add_u32 s98, s98, s99
	v_lshlrev_b32_e32 v86, 10, v192
	v_lshl_add_u32 v86, v193, 1, v86
	v_add_u32_e32 v86, s98, v86
	v_lshl_add_u32 v87, v192, 5, v193
	v_lshrrev_b32_e32 v88, 4, v87
	v_and_b32_e32 v89, 15, v87
	v_lshlrev_b32_e32 v90, 8, v88
	v_lshl_add_u32 v90, v89, 4, v90
	v_add_u32_e32 v90, s98, v90
	v_lshlrev_b32_e32 v85, 12, v170
	v_lshl_add_u32 v85, v88, 12, v85
	v_lshl_add_u32 v85, v89, 4, v85
	v_cvt_pk_bf16_f32 v116, v0, v0
	v_cvt_pk_bf16_f32 v117, v48, v48
	v_cvt_pk_bf16_f32 v118, v32, v32
	v_cvt_pk_bf16_f32 v119, v16, v16
	ds_write_b16 v86, v116 offset:0
	ds_write_b16 v86, v117 offset:64
	ds_write_b16 v86, v118 offset:128
	ds_write_b16 v86, v119 offset:192
	v_cvt_pk_bf16_f32 v116, v1, v1
	v_cvt_pk_bf16_f32 v117, v49, v49
	v_cvt_pk_bf16_f32 v118, v33, v33
	v_cvt_pk_bf16_f32 v119, v17, v17
	ds_write_b16 v86, v116 offset:256
	ds_write_b16 v86, v117 offset:320
	ds_write_b16 v86, v118 offset:384
	ds_write_b16 v86, v119 offset:448
	v_cvt_pk_bf16_f32 v116, v2, v2
	v_cvt_pk_bf16_f32 v117, v50, v50
	v_cvt_pk_bf16_f32 v118, v34, v34
	v_cvt_pk_bf16_f32 v119, v18, v18
	ds_write_b16 v86, v116 offset:512
	ds_write_b16 v86, v117 offset:576
	ds_write_b16 v86, v118 offset:640
	ds_write_b16 v86, v119 offset:704
	v_cvt_pk_bf16_f32 v116, v3, v3
	v_cvt_pk_bf16_f32 v117, v51, v51
	v_cvt_pk_bf16_f32 v118, v35, v35
	v_cvt_pk_bf16_f32 v119, v19, v19
	ds_write_b16 v86, v116 offset:768
	ds_write_b16 v86, v117 offset:832
	ds_write_b16 v86, v118 offset:896
	ds_write_b16 v86, v119 offset:960
	v_cvt_pk_bf16_f32 v116, v4, v4
	v_cvt_pk_bf16_f32 v117, v52, v52
	v_cvt_pk_bf16_f32 v118, v36, v36
	v_cvt_pk_bf16_f32 v119, v20, v20
	ds_write_b16 v86, v116 offset:2048
	ds_write_b16 v86, v117 offset:2112
	ds_write_b16 v86, v118 offset:2176
	ds_write_b16 v86, v119 offset:2240
	v_cvt_pk_bf16_f32 v116, v5, v5
	v_cvt_pk_bf16_f32 v117, v53, v53
	v_cvt_pk_bf16_f32 v118, v37, v37
	v_cvt_pk_bf16_f32 v119, v21, v21
	ds_write_b16 v86, v116 offset:2304
	ds_write_b16 v86, v117 offset:2368
	ds_write_b16 v86, v118 offset:2432
	ds_write_b16 v86, v119 offset:2496
	v_cvt_pk_bf16_f32 v116, v6, v6
	v_cvt_pk_bf16_f32 v117, v54, v54
	v_cvt_pk_bf16_f32 v118, v38, v38
	v_cvt_pk_bf16_f32 v119, v22, v22
	ds_write_b16 v86, v116 offset:2560
	ds_write_b16 v86, v117 offset:2624
	ds_write_b16 v86, v118 offset:2688
	ds_write_b16 v86, v119 offset:2752
	v_cvt_pk_bf16_f32 v116, v7, v7
	v_cvt_pk_bf16_f32 v117, v55, v55
	v_cvt_pk_bf16_f32 v118, v39, v39
	v_cvt_pk_bf16_f32 v119, v23, v23
	ds_write_b16 v86, v116 offset:2816
	ds_write_b16 v86, v117 offset:2880
	ds_write_b16 v86, v118 offset:2944
	ds_write_b16 v86, v119 offset:3008
	v_cvt_pk_bf16_f32 v116, v8, v8
	v_cvt_pk_bf16_f32 v117, v56, v56
	v_cvt_pk_bf16_f32 v118, v40, v40
	v_cvt_pk_bf16_f32 v119, v24, v24
	ds_write_b16 v86, v116 offset:4096
	ds_write_b16 v86, v117 offset:4160
	ds_write_b16 v86, v118 offset:4224
	ds_write_b16 v86, v119 offset:4288
	v_cvt_pk_bf16_f32 v116, v9, v9
	v_cvt_pk_bf16_f32 v117, v57, v57
	v_cvt_pk_bf16_f32 v118, v41, v41
	v_cvt_pk_bf16_f32 v119, v25, v25
	ds_write_b16 v86, v116 offset:4352
	ds_write_b16 v86, v117 offset:4416
	ds_write_b16 v86, v118 offset:4480
	ds_write_b16 v86, v119 offset:4544
	v_cvt_pk_bf16_f32 v116, v10, v10
	v_cvt_pk_bf16_f32 v117, v58, v58
	v_cvt_pk_bf16_f32 v118, v42, v42
	v_cvt_pk_bf16_f32 v119, v26, v26
	ds_write_b16 v86, v116 offset:4608
	ds_write_b16 v86, v117 offset:4672
	ds_write_b16 v86, v118 offset:4736
	ds_write_b16 v86, v119 offset:4800
	v_cvt_pk_bf16_f32 v116, v11, v11
	v_cvt_pk_bf16_f32 v117, v59, v59
	v_cvt_pk_bf16_f32 v118, v43, v43
	v_cvt_pk_bf16_f32 v119, v27, v27
	ds_write_b16 v86, v116 offset:4864
	ds_write_b16 v86, v117 offset:4928
	ds_write_b16 v86, v118 offset:4992
	ds_write_b16 v86, v119 offset:5056
	v_cvt_pk_bf16_f32 v116, v12, v12
	v_cvt_pk_bf16_f32 v117, v60, v60
	v_cvt_pk_bf16_f32 v118, v44, v44
	v_cvt_pk_bf16_f32 v119, v28, v28
	ds_write_b16 v86, v116 offset:6144
	ds_write_b16 v86, v117 offset:6208
	ds_write_b16 v86, v118 offset:6272
	ds_write_b16 v86, v119 offset:6336
	v_cvt_pk_bf16_f32 v116, v13, v13
	v_cvt_pk_bf16_f32 v117, v61, v61
	v_cvt_pk_bf16_f32 v118, v45, v45
	v_cvt_pk_bf16_f32 v119, v29, v29
	ds_write_b16 v86, v116 offset:6400
	ds_write_b16 v86, v117 offset:6464
	ds_write_b16 v86, v118 offset:6528
	ds_write_b16 v86, v119 offset:6592
	v_cvt_pk_bf16_f32 v116, v14, v14
	v_cvt_pk_bf16_f32 v117, v62, v62
	v_cvt_pk_bf16_f32 v118, v46, v46
	v_cvt_pk_bf16_f32 v119, v30, v30
	ds_write_b16 v86, v116 offset:6656
	ds_write_b16 v86, v117 offset:6720
	ds_write_b16 v86, v118 offset:6784
	ds_write_b16 v86, v119 offset:6848
	v_cvt_pk_bf16_f32 v116, v15, v15
	v_cvt_pk_bf16_f32 v117, v63, v63
	v_cvt_pk_bf16_f32 v118, v47, v47
	v_cvt_pk_bf16_f32 v119, v31, v31
	ds_write_b16 v86, v116 offset:6912
	ds_write_b16 v86, v117 offset:6976
	ds_write_b16 v86, v118 offset:7040
	ds_write_b16 v86, v119 offset:7104
	s_waitcnt lgkmcnt(0)
; template <int MASK> __device__ __forceinline__ float xor_get(float v) { return __int_as_float(__builtin_amdgcn_ds_swizzle(__float_as_int(v), 0x1F | (MASK << 10))); }
; __device__ __forceinline__ void ss_add(u64* p, float v) { atomicAdd(p, (u64)(v * SSFIX)); }
; __device__ __forceinline__ int crow(int r, int hi) { return (r & 3) + 8 * (r >> 2) + 4 * hi; }
; __device__ __forceinline__ unsigned cvtpk(float lo, float hi) { unsigned r; asm volatile("v_cvt_pk_bf16_f32 %0, %1, %2" : "=v"(r) : "v"(lo), "v"(hi)); return r; }
; __device__ __forceinline__ void attn_dense_body(const bf16* __restrict__ Qb, const bf16* __restrict__ Kn, const bf16* __restrict__ Kr, const bf16* __restrict__ Vh,
;                                                 bf16* __restrict__ Ob, pg8::u64* ssa, int seq, char* lds, const int wv) {
;     ...
;   for (int r = 0; r < 16; ++r) { int orow = crow(r, hi);
;     float sq = 0.f;
; #pragma unroll
;     for (int d0 = 0; d0 < 4; ++d0) { const float v = o[d0][r] * rli[r]; sq += v * v; Ow[(long)orow * LDO + d0 * 32 + r32] = (bf16)(cvtpk(v, 0.f) & 0xffffu); }
;     sq += xor_get<1>(sq); sq += xor_get<2>(sq); sq += xor_get<4>(sq); sq += xor_get<8>(sq); sq += xor_get<16>(sq);
;     if (r32 == 0) pg8::ss_add(ssa + wid * QBLK + orow, sq); }
	ds_read_b128 v[0:3], v90 offset:0
	ds_read_b128 v[4:7], v90 offset:1024
	ds_read_b128 v[8:11], v90 offset:2048
	ds_read_b128 v[12:15], v90 offset:3072
	ds_read_b128 v[16:19], v90 offset:4096
	ds_read_b128 v[20:23], v90 offset:5120
	ds_read_b128 v[24:27], v90 offset:6144
	ds_read_b128 v[28:31], v90 offset:7168
	s_mov_b32 s98, s4
	s_mov_b32 s99, s5
	s_waitcnt lgkmcnt(7)
	global_store_dwordx4 v85, v[0:3], s[98:99]
	s_add_u32 s98, s4, 0x4000
	s_addc_u32 s99, s5, 0
	s_waitcnt lgkmcnt(6)
	global_store_dwordx4 v85, v[4:7], s[98:99]
	s_add_u32 s98, s4, 0x8000
	s_addc_u32 s99, s5, 0
	s_waitcnt lgkmcnt(5)
	global_store_dwordx4 v85, v[8:11], s[98:99]
	s_add_u32 s98, s4, 0xc000
	s_addc_u32 s99, s5, 0
	s_waitcnt lgkmcnt(4)
	global_store_dwordx4 v85, v[12:15], s[98:99]
	s_add_u32 s98, s4, 0x10000
	s_addc_u32 s99, s5, 0
	s_waitcnt lgkmcnt(3)
	global_store_dwordx4 v85, v[16:19], s[98:99]
	s_add_u32 s98, s4, 0x14000
	s_addc_u32 s99, s5, 0
	s_waitcnt lgkmcnt(2)
	global_store_dwordx4 v85, v[20:23], s[98:99]
	s_add_u32 s98, s4, 0x18000
	s_addc_u32 s99, s5, 0
	s_waitcnt lgkmcnt(1)
	global_store_dwordx4 v85, v[24:27], s[98:99]
	s_add_u32 s98, s4, 0x1c000
	s_addc_u32 s99, s5, 0
	s_waitcnt lgkmcnt(0)
	global_store_dwordx4 v85, v[28:31], s[98:99]
	s_and_saveexec_b64 s[2:3], vcc
	s_cbranch_execz .LBB0_1150
	v_mul_f32_e32 v96, 0x49800000, v96
	v_trunc_f32_e32 v96, v96
	v_mul_f32_e32 v113, 0x2f800000, v96
	v_floor_f32_e32 v113, v113
	v_fmac_f32_e32 v96, 0xcf800000, v113
	v_cvt_u32_f32_e32 v112, v96
	v_cvt_u32_f32_e32 v113, v113
	global_atomic_add_x2 v[80:81], v[112:113], off
	s_nop 1
	v_mul_f32_e32 v97, 0x49800000, v97
	v_trunc_f32_e32 v97, v97
	v_mul_f32_e32 v113, 0x2f800000, v97
	v_floor_f32_e32 v113, v113
	v_fmac_f32_e32 v97, 0xcf800000, v113
	v_cvt_u32_f32_e32 v112, v97
	v_cvt_u32_f32_e32 v113, v113
	global_atomic_add_x2 v[80:81], v[112:113], off offset:8
	s_nop 1
	v_mul_f32_e32 v98, 0x49800000, v98
	v_trunc_f32_e32 v98, v98
	v_mul_f32_e32 v113, 0x2f800000, v98
	v_floor_f32_e32 v113, v113
	v_fmac_f32_e32 v98, 0xcf800000, v113
	v_cvt_u32_f32_e32 v112, v98
	v_cvt_u32_f32_e32 v113, v113
	global_atomic_add_x2 v[80:81], v[112:113], off offset:16
	s_nop 1
	v_mul_f32_e32 v99, 0x49800000, v99
	v_trunc_f32_e32 v99, v99
	v_mul_f32_e32 v113, 0x2f800000, v99
	v_floor_f32_e32 v113, v113
	v_fmac_f32_e32 v99, 0xcf800000, v113
	v_cvt_u32_f32_e32 v112, v99
	v_cvt_u32_f32_e32 v113, v113
	global_atomic_add_x2 v[80:81], v[112:113], off offset:24
	s_nop 1
	v_mul_f32_e32 v100, 0x49800000, v100
	v_trunc_f32_e32 v100, v100
	v_mul_f32_e32 v113, 0x2f800000, v100
	v_floor_f32_e32 v113, v113
	v_fmac_f32_e32 v100, 0xcf800000, v113
	v_cvt_u32_f32_e32 v112, v100
	v_cvt_u32_f32_e32 v113, v113
	global_atomic_add_x2 v[80:81], v[112:113], off offset:64
	s_nop 1
	v_mul_f32_e32 v101, 0x49800000, v101
	v_trunc_f32_e32 v101, v101
	v_mul_f32_e32 v113, 0x2f800000, v101
	v_floor_f32_e32 v113, v113
	v_fmac_f32_e32 v101, 0xcf800000, v113
	v_cvt_u32_f32_e32 v112, v101
	v_cvt_u32_f32_e32 v113, v113
	global_atomic_add_x2 v[80:81], v[112:113], off offset:72
	s_nop 1
	v_mul_f32_e32 v102, 0x49800000, v102
	v_trunc_f32_e32 v102, v102
	v_mul_f32_e32 v113, 0x2f800000, v102
	v_floor_f32_e32 v113, v113
	v_fmac_f32_e32 v102, 0xcf800000, v113
	v_cvt_u32_f32_e32 v112, v102
	v_cvt_u32_f32_e32 v113, v113
	global_atomic_add_x2 v[80:81], v[112:113], off offset:80
	s_nop 1
	v_mul_f32_e32 v103, 0x49800000, v103
	v_trunc_f32_e32 v103, v103
	v_mul_f32_e32 v113, 0x2f800000, v103
	v_floor_f32_e32 v113, v113
	v_fmac_f32_e32 v103, 0xcf800000, v113
	v_cvt_u32_f32_e32 v112, v103
	v_cvt_u32_f32_e32 v113, v113
	global_atomic_add_x2 v[80:81], v[112:113], off offset:88
	s_nop 1
	v_mul_f32_e32 v104, 0x49800000, v104
	v_trunc_f32_e32 v104, v104
	v_mul_f32_e32 v113, 0x2f800000, v104
	v_floor_f32_e32 v113, v113
	v_fmac_f32_e32 v104, 0xcf800000, v113
	v_cvt_u32_f32_e32 v112, v104
	v_cvt_u32_f32_e32 v113, v113
	global_atomic_add_x2 v[80:81], v[112:113], off offset:128
	s_nop 1
	v_mul_f32_e32 v105, 0x49800000, v105
	v_trunc_f32_e32 v105, v105
	v_mul_f32_e32 v113, 0x2f800000, v105
	v_floor_f32_e32 v113, v113
	v_fmac_f32_e32 v105, 0xcf800000, v113
	v_cvt_u32_f32_e32 v112, v105
	v_cvt_u32_f32_e32 v113, v113
	global_atomic_add_x2 v[80:81], v[112:113], off offset:136
	s_nop 1
	v_mul_f32_e32 v106, 0x49800000, v106
	v_trunc_f32_e32 v106, v106
	v_mul_f32_e32 v113, 0x2f800000, v106
	v_floor_f32_e32 v113, v113
	v_fmac_f32_e32 v106, 0xcf800000, v113
	v_cvt_u32_f32_e32 v112, v106
	v_cvt_u32_f32_e32 v113, v113
	global_atomic_add_x2 v[80:81], v[112:113], off offset:144
	s_nop 1
	v_mul_f32_e32 v107, 0x49800000, v107
	v_trunc_f32_e32 v107, v107
	v_mul_f32_e32 v113, 0x2f800000, v107
	v_floor_f32_e32 v113, v113
	v_fmac_f32_e32 v107, 0xcf800000, v113
	v_cvt_u32_f32_e32 v112, v107
	v_cvt_u32_f32_e32 v113, v113
	global_atomic_add_x2 v[80:81], v[112:113], off offset:152
	s_nop 1
	v_mul_f32_e32 v108, 0x49800000, v108
	v_trunc_f32_e32 v108, v108
	v_mul_f32_e32 v113, 0x2f800000, v108
	v_floor_f32_e32 v113, v113
	v_fmac_f32_e32 v108, 0xcf800000, v113
	v_cvt_u32_f32_e32 v112, v108
	v_cvt_u32_f32_e32 v113, v113
	global_atomic_add_x2 v[80:81], v[112:113], off offset:192
	s_nop 1
	v_mul_f32_e32 v109, 0x49800000, v109
	v_trunc_f32_e32 v109, v109
	v_mul_f32_e32 v113, 0x2f800000, v109
	v_floor_f32_e32 v113, v113
	v_fmac_f32_e32 v109, 0xcf800000, v113
	v_cvt_u32_f32_e32 v112, v109
	v_cvt_u32_f32_e32 v113, v113
	global_atomic_add_x2 v[80:81], v[112:113], off offset:200
	s_nop 1
	v_mul_f32_e32 v110, 0x49800000, v110
	v_trunc_f32_e32 v110, v110
	v_mul_f32_e32 v113, 0x2f800000, v110
	v_floor_f32_e32 v113, v113
	v_fmac_f32_e32 v110, 0xcf800000, v113
	v_cvt_u32_f32_e32 v112, v110
	v_cvt_u32_f32_e32 v113, v113
	global_atomic_add_x2 v[80:81], v[112:113], off offset:208
	s_nop 1
	v_mul_f32_e32 v111, 0x49800000, v111
	v_trunc_f32_e32 v111, v111
	v_mul_f32_e32 v113, 0x2f800000, v111
	v_floor_f32_e32 v113, v113
	v_fmac_f32_e32 v111, 0xcf800000, v113
	v_cvt_u32_f32_e32 v112, v111
	v_cvt_u32_f32_e32 v113, v113
	global_atomic_add_x2 v[80:81], v[112:113], off offset:216
	s_nop 1
	s_branch .LBB0_1150
